# rpb/subln gain staging loads issued inside the GEMM0->attention barrier; local barrier invalidates L1 before arriving instead of after
# speedup vs baseline: 1.1068x; 1.0076x over previous
; __global__ void __launch_bounds__(NTHREADS) fwd_megakernel(Params p) {
;     ...
;         { int t0_ = threadIdx.x; asm volatile("" : "+v"(t0_));
;           for (int i = t0_; i < 8 * 465; i += NTHREADS) ((float*)(lds + LDS_RPB_OFF))[i] = p.rpb[(size_t)layer * 8 * 465 + i] * LOG2E;
;           if (t0_ < 128) ((float*)(lds + LDS_SG_OFF))[t0_] = p.subln_g[layer * 128 + t0_];
.LBB0_379:
	s_waitcnt vmcnt(0)
	s_waitcnt vmcnt(63) expcnt(7) lgkmcnt(15)
	s_barrier
	v_readlane_b32 s34, v254, 0
	v_readlane_b32 s35, v254, 1
	s_load_dwordx4 s[40:43], s[34:35], 0x40
	v_readlane_b32 s38, v254, 58
	s_mul_i32 s39, s38, 0x3a20
	s_lshl_b32 s38, s38, 9
	v_lshlrev_b32_e32 v253, 2, v245
	s_waitcnt lgkmcnt(0)
	s_add_u32 s42, s42, s39
	s_addc_u32 s43, s43, 0
	s_add_u32 s40, s40, s38
	s_addc_u32 s41, s41, 0
	global_load_dword v193, v253, s[42:43]
	s_add_u32 s42, s42, 0x800
	s_addc_u32 s43, s43, 0
	global_load_dword v194, v253, s[42:43]
	s_add_u32 s42, s42, 0x800
	s_addc_u32 s43, s43, 0
	global_load_dword v202, v253, s[42:43]
	s_add_u32 s42, s42, 0x800
	s_addc_u32 s43, s43, 0
	global_load_dword v203, v253, s[42:43]
	s_add_u32 s42, s42, 0x800
	s_addc_u32 s43, s43, 0
	global_load_dword v234, v253, s[42:43]
	s_add_u32 s42, s42, 0x800
	s_addc_u32 s43, s43, 0
	global_load_dword v235, v253, s[42:43]
	s_add_u32 s42, s42, 0x800
	s_addc_u32 s43, s43, 0
	global_load_dword v239, v253, s[42:43]
	s_add_u32 s42, s42, 0x800
	s_addc_u32 s43, s43, 0
	s_movk_i32 s46, 0x88
	v_cmp_gt_u32_e64 s[28:29], s46, v245
	s_and_saveexec_b64 s[44:45], s[28:29]
	global_load_dword v241, v253, s[42:43]
	s_mov_b64 exec, s[44:45]
	s_movk_i32 s46, 0x80
	v_cmp_gt_u32_e64 s[28:29], s46, v245
	s_and_saveexec_b64 s[44:45], s[28:29]
	global_load_dword v242, v253, s[40:41]
	s_mov_b64 exec, s[44:45]
	s_mov_b32 s23, 0
	v_readlane_b32 s39, v254, 58
	s_cmp_gt_u32 s39, 2
	s_cbranch_scc1 .Lwc_iskip_s2
	s_add_i32 s39, s39, 1
	v_readfirstlane_b32 s38, v245
	s_lshr_b32 s38, s38, 6
	s_sub_u32 s38, s38, 1
	s_cmp_gt_u32 s38, 3
	s_cbranch_scc1 .Lwc_iskip_s2
	s_add_i32 s38, s38, 4
	v_readlane_b32 s34, v254, 0
	v_readlane_b32 s35, v254, 1
	s_load_dwordx4 s[28:31], s[34:35], 0x8
	s_load_dwordx2 s[32:33], s[34:35], 0x18
	s_load_dwordx4 s[40:43], s[34:35], 0x60
	v_and_b32_e32 v190, 63, v245
	v_lshrrev_b32_e32 v191, 3, v190
	v_and_b32_e32 v190, 7, v190
	v_lshlrev_b32_e32 v186, 17, v191
	v_lshl_add_u32 v186, v190, 4, v186
	v_lshlrev_b32_e32 v187, 13, v190
	v_lshl_add_u32 v187, v191, 4, v187
	v_lshlrev_b32_e32 v188, 5, v191
	v_lshlrev_b32_e32 v189, 15, v191
	v_lshl_add_u32 v189, v190, 2, v189
	v_lshlrev_b32_e32 v192, 11, v190
	v_lshl_add_u32 v192, v191, 4, v192
	s_lshr_b32 s44, s84, 7
	s_lshl_b32 s46, s38, 1
	s_add_i32 s44, s44, s46
	s_and_b32 s45, s84, 0x7f
	s_lshl_b32 s46, s45, 5
	s_mov_b32 s38, 0
	s_cmpk_ge_u32 s46, 0x400
	s_cselect_b32 s38, 0x200, s38
	s_cmpk_ge_u32 s46, 0x800
	s_cselect_b32 s38, 0x400, s38
	s_cmpk_ge_u32 s46, 0xc00
	s_cselect_b32 s38, 0xfffff800, s38
	s_cmpk_ge_u32 s46, 0xe00
	s_cselect_b32 s38, 0xfffffc00, s38
	s_add_i32 s38, s46, s38
	s_waitcnt lgkmcnt(0)
	s_lshl_b32 s38, s38, 2
	s_lshl_b32 s34, s39, 24
	s_add_u32 s38, s38, s34
	s_lshl_b32 s34, s44, 20
	s_add_u32 s38, s38, s34
	s_add_u32 s30, s30, s38
	s_addc_u32 s31, s31, 0
	s_lshl_b32 s34, s39, 12
	s_lshl_b32 s35, s44, 8
	s_add_i32 s34, s34, s35
	s_add_u32 s28, s28, s34
	s_addc_u32 s29, s29, 0
	s_lshl_b32 s34, s39, 23
	s_lshl_b32 s35, s46, 11
	s_add_u32 s34, s34, s35
	s_lshl_b32 s35, s44, 7
	s_add_u32 s34, s34, s35
	s_addk_i32 s34, 0x1000
	s_add_u32 s24, s40, s34
	s_addc_u32 s25, s41, 0
	s_lshl_b32 s34, s39, 22
	s_lshl_b32 s35, s44, 18
	s_add_u32 s34, s34, s35
	s_lshl_b32 s35, s45, 5
	s_add_u32 s34, s34, s35
	s_add_u32 s32, s32, s34
	s_addc_u32 s33, s33, 0
	s_lshl_b32 s34, s39, 21
	s_lshl_b32 s35, s45, 14
	s_add_u32 s34, s34, s35
	s_lshl_b32 s35, s44, 7
	s_add_u32 s34, s34, s35
	s_add_u32 s26, s42, s34
	s_addc_u32 s27, s43, 0
	global_load_dwordx4 v[104:107], v188, s[28:29]
	global_load_dwordx4 v[108:111], v188, s[28:29] offset:16
	global_load_dwordx4 v[72:75], v186, s[30:31]
	s_add_u32 s30, s30, 0x4000
	s_addc_u32 s31, s31, 0
	global_load_dwordx4 v[76:79], v186, s[30:31]
	s_add_u32 s30, s30, 0x4000
	s_addc_u32 s31, s31, 0
	global_load_dwordx4 v[80:83], v186, s[30:31]
	s_add_u32 s30, s30, 0x4000
	s_addc_u32 s31, s31, 0
	global_load_dwordx4 v[84:87], v186, s[30:31]
	s_add_u32 s30, s30, 0x4000
	s_addc_u32 s31, s31, 0
	global_load_dwordx4 v[88:91], v186, s[30:31]
	s_add_u32 s30, s30, 0x4000
	s_addc_u32 s31, s31, 0
	global_load_dwordx4 v[92:95], v186, s[30:31]
	s_add_u32 s30, s30, 0x4000
	s_addc_u32 s31, s31, 0
	global_load_dwordx4 v[96:99], v186, s[30:31]
	s_add_u32 s30, s30, 0x4000
	s_addc_u32 s31, s31, 0
	global_load_dwordx4 v[100:103], v186, s[30:31]
	global_load_dword v218, v189, s[32:33]
	s_add_u32 s32, s32, 0x1000
	s_addc_u32 s33, s33, 0
	global_load_dword v219, v189, s[32:33]
	s_add_u32 s32, s32, 0x1000
	s_addc_u32 s33, s33, 0
	global_load_dword v220, v189, s[32:33]
	s_add_u32 s32, s32, 0x1000
	s_addc_u32 s33, s33, 0
	global_load_dword v221, v189, s[32:33]
	s_add_u32 s32, s32, 0x1000
	s_addc_u32 s33, s33, 0
	global_load_dword v222, v189, s[32:33]
	s_add_u32 s32, s32, 0x1000
	s_addc_u32 s33, s33, 0
	global_load_dword v223, v189, s[32:33]
	s_add_u32 s32, s32, 0x1000
	s_addc_u32 s33, s33, 0
	global_load_dword v224, v189, s[32:33]
	s_add_u32 s32, s32, 0x1000
	s_addc_u32 s33, s33, 0
	global_load_dword v225, v189, s[32:33]
	s_mov_b32 s23, 1

; __device__ __forceinline__ unsigned xb_ld(unsigned* p)              { return __hip_atomic_load(p, __ATOMIC_RELAXED, __HIP_MEMORY_SCOPE_AGENT); }
; __device__ __forceinline__ unsigned xb_add(unsigned* p, unsigned v) { return __hip_atomic_fetch_add(p, v, __ATOMIC_RELAXED, __HIP_MEMORY_SCOPE_AGENT); }
; #define XB_SPIN(cond, bar) do { unsigned _sp = 0; while (cond) { __builtin_amdgcn_s_sleep(1); \
;     if ((++_sp & 255u) == 0u) { if (xb_ld(&(bar)[XB_TMO])) break; if (_sp > XB_SPIN_CAP) { atomicAdd(&(bar)[XB_TMO], 1u); break; } } } } while (0)
; __device__ __forceinline__ void xcd_barrier(const XcdBarrier& b) {
;     ...
;             __builtin_amdgcn_fence(__ATOMIC_ACQUIRE, "agent");
;             xb_add(&bar[XB_XGEN(bx)], 1u);
;             asm volatile("s_waitcnt vmcnt(0)" ::: "memory");
;         } else {
;             XB_SPIN(xb_ld(&bar[XB_XGEN(bx)]) == gen, bar);
;             __builtin_amdgcn_fence(__ATOMIC_ACQUIRE, "agent");
.Lwc_pskip_2:
	s_cmp_eq_u32 s99, 0
	s_cbranch_scc1 .Lxb_full_1
	v_readlane_b32 s2, v254, 2
	v_mov_b32_e32 v1, 1
	s_lshl_b32 s2, s2, 8
	s_mov_b32 s98, 0
	v_mov_b32_e32 v0, s2
	buffer_inv sc1
	global_atomic_add v1, v0, v1, s[82:83] offset:1152 sc0
	s_waitcnt vmcnt(0)
	v_lshrrev_b32_e32 v1, 5, v1
	v_add_u32_e32 v1, 1, v1
	v_lshlrev_b32_e32 v1, 5, v1

; __device__ __forceinline__ void xcd_barrier(const XcdBarrier& b) {
;     ...
;             __builtin_amdgcn_fence(__ATOMIC_ACQUIRE, "agent");
;             asm volatile("s_waitcnt vmcnt(0)" ::: "memory");
.Lxb_done_1:
	s_branch .LBB0_431

; __global__ void __launch_bounds__(NTHREADS) fwd_megakernel(Params p) {
;     ...
;         { int t0_ = threadIdx.x; asm volatile("" : "+v"(t0_));
;           for (int i = t0_; i < 8 * 465; i += NTHREADS) ((float*)(lds + LDS_RPB_OFF))[i] = p.rpb[(size_t)layer * 8 * 465 + i] * LOG2E;
;           if (t0_ < 128) ((float*)(lds + LDS_SG_OFF))[t0_] = p.subln_g[layer * 128 + t0_];
;           if (t0_ == 0) *(volatile unsigned*)(lds + LDS_PHASE_BYTES + 12) = 0u; }
.Lwc_cskip_s2:
	s_waitcnt vmcnt(0)
	v_add_u32_e32 v252, 0x23090, v253
	v_mul_f32_e32 v193, 0x3fb8aa3b, v193
	ds_write_b32 v252, v193
	v_mul_f32_e32 v194, 0x3fb8aa3b, v194
	ds_write_b32 v252, v194 offset:2048
	v_mul_f32_e32 v202, 0x3fb8aa3b, v202
	ds_write_b32 v252, v202 offset:4096
	v_mul_f32_e32 v203, 0x3fb8aa3b, v203
	ds_write_b32 v252, v203 offset:6144
	v_mul_f32_e32 v234, 0x3fb8aa3b, v234
	ds_write_b32 v252, v234 offset:8192
	v_mul_f32_e32 v235, 0x3fb8aa3b, v235
	ds_write_b32 v252, v235 offset:10240
	v_mul_f32_e32 v239, 0x3fb8aa3b, v239
	ds_write_b32 v252, v239 offset:12288
	s_movk_i32 s4, 0x88
	v_cmp_gt_u32_e64 s[2:3], s4, v245
	s_and_saveexec_b64 s[0:1], s[2:3]
	v_mul_f32_e32 v241, 0x3fb8aa3b, v241
	ds_write_b32 v252, v241 offset:14336
	s_mov_b64 exec, s[0:1]
	s_movk_i32 s4, 0x80
	v_cmp_gt_u32_e64 s[2:3], s4, v245
	s_and_saveexec_b64 s[0:1], s[2:3]
	v_add_u32_e32 v248, 0x26b30, v253
	ds_write_b32 v248, v242
	s_mov_b64 exec, s[0:1]
	v_cmp_eq_u32_e64 s[2:3], 0, v245
	s_and_saveexec_b64 s[0:1], s[2:3]
	v_mov_b32_e32 v248, 0x2300c
	v_mov_b32_e32 v249, 0
	ds_write_b32 v248, v249
	s_mov_b64 exec, s[0:1]
	v_readlane_b32 s3, v254, 59
	v_readlane_b32 s0, v254, 14
	v_readlane_b32 s1, v254, 15
	s_andn2_b64 vcc, exec, s[0:1]
	s_waitcnt lgkmcnt(0)
	s_barrier
	s_cbranch_vccnz .LBB0_531
	v_readlane_b32 s0, v254, 58
	v_readlane_b32 s1, v254, 59
	s_mov_b32 s2, s0
	s_lshl_b32 s1, s0, 6
	v_writelane_b32 v254, s2, 58
	v_writelane_b32 v255, s1, 36
	s_mov_b32 s1, s71
	v_writelane_b32 v254, s3, 59
	s_lshl_b64 s[0:1], s[0:1], 2
	v_readlane_b32 s2, v254, 0
	v_readlane_b32 s3, v254, 1
	s_add_u32 s86, s2, s0
	s_addc_u32 s87, s3, s1
	s_mov_b32 s21, s84
	s_branch .LBB0_452

; __device__ __forceinline__ unsigned xb_ld(unsigned* p)              { return __hip_atomic_load(p, __ATOMIC_RELAXED, __HIP_MEMORY_SCOPE_AGENT); }
; __device__ __forceinline__ unsigned xb_add(unsigned* p, unsigned v) { return __hip_atomic_fetch_add(p, v, __ATOMIC_RELAXED, __HIP_MEMORY_SCOPE_AGENT); }
; #define XB_SPIN(cond, bar) do { unsigned _sp = 0; while (cond) { __builtin_amdgcn_s_sleep(1); \
;     if ((++_sp & 255u) == 0u) { if (xb_ld(&(bar)[XB_TMO])) break; if (_sp > XB_SPIN_CAP) { atomicAdd(&(bar)[XB_TMO], 1u); break; } } } } while (0)
; __device__ __forceinline__ void xcd_barrier(const XcdBarrier& b) {
;     ...
;             __builtin_amdgcn_fence(__ATOMIC_ACQUIRE, "agent");
;             xb_add(&bar[XB_XGEN(bx)], 1u);
;             asm volatile("s_waitcnt vmcnt(0)" ::: "memory");
;         } else {
;             XB_SPIN(xb_ld(&bar[XB_XGEN(bx)]) == gen, bar);
;             __builtin_amdgcn_fence(__ATOMIC_ACQUIRE, "agent");
.Lwc_iskip_a4:
	s_and_saveexec_b64 s[0:1], s[66:67]
	s_cbranch_execz .LBB0_101
	v_mov_b32_e32 v61, 0
	global_load_dword v60, v61, s[82:83] offset:256 sc1
	s_cmp_eq_u32 s99, 0
	s_cbranch_scc1 .Lxb_full_3
	v_readlane_b32 s2, v254, 2
	v_mov_b32_e32 v1, 1
	s_lshl_b32 s2, s2, 8
	s_mov_b32 s98, 0
	v_mov_b32_e32 v0, s2
	buffer_inv sc1
	global_atomic_add v1, v0, v1, s[82:83] offset:1152 sc0
	s_waitcnt vmcnt(0)
	v_lshrrev_b32_e32 v1, 5, v1
	v_add_u32_e32 v1, 1, v1
	v_lshlrev_b32_e32 v1, 5, v1
